# P1: per row the 9 later parameter loads issued with the first three (one parameter round trip and one store drain per row instead of four)
# baseline (speedup 1.0000x reference)
.LBB0_145:
	s_or_b64 exec, exec, s[6:7]
	v_min_i32_e32 v97, 0x10000, v95
	v_ashrrev_i32_e32 v97, 12, v97
	v_mul_i32_i24_e32 v98, 0x1800, v97
	v_ashrrev_i32_e32 v99, 31, v98
	v_lshl_add_u64 v[98:99], v[98:99], 2, s[24:25]
	v_lshl_add_u64 v[112:113], v[98:99], 0, v[66:67]
	v_add_co_u32_e64 v102, s[0:1], s63, v112
	v_lshl_add_u64 v[156:157], v[112:113], 0, s[36:37]
	global_load_dwordx4 v[120:123], v[72:73], off offset:1024
	global_load_dwordx4 v[124:127], v[156:157], off offset:1024
	global_load_dwordx4 v[128:131], v[112:113], off offset:1024
	global_load_dwordx4 v[132:135], v[72:73], off offset:2048
	global_load_dwordx4 v[136:139], v[156:157], off offset:2048
	global_load_dwordx4 v[140:143], v[112:113], off offset:2048
	global_load_dwordx4 v[144:147], v[72:73], off offset:3072
	global_load_dwordx4 v[148:151], v[156:157], off offset:3072
	global_load_dwordx4 v[152:155], v[112:113], off offset:3072
	global_load_dwordx4 v[98:101], v[72:73], off
	s_nop 0
	v_addc_co_u32_e64 v103, s[0:1], 0, v113, s[0:1]
	global_load_dwordx4 v[102:105], v[102:103], off
	s_waitcnt vmcnt(14)
	v_pk_mul_f32 v[110:111], v[62:63], v[62:63]
	global_load_dwordx4 v[106:109], v[112:113], off
	v_pk_mul_f32 v[114:115], v[60:61], v[60:61]
	s_waitcnt vmcnt(12)
	v_mul_f32_e32 v97, v48, v48
	v_pk_mov_b32 v[116:117], v[114:115], v[110:111] op_sel:[1,0]
	v_mov_b32_e32 v115, v111
	v_pk_add_f32 v[110:111], v[116:117], v[114:115]
	v_pk_mul_f32 v[114:115], v[58:59], v[58:59]
	v_pk_mul_f32 v[116:117], v[56:57], v[56:57]
	v_pk_add_f32 v[110:111], v[110:111], v[110:111] op_sel:[0,1] op_sel_hi:[1,0]
	v_pk_mov_b32 v[118:119], v[116:117], v[114:115] op_sel:[1,0]
	v_mov_b32_e32 v117, v115
	v_pk_add_f32 v[114:115], v[118:119], v[116:117]
	v_mul_f32_e32 v116, v49, v49
	v_pk_add_f32 v[114:115], v[114:115], v[114:115] op_sel:[0,1] op_sel_hi:[1,0]
	v_mov_b32_e32 v111, v97
	v_mov_b32_e32 v115, v116
	v_pk_add_f32 v[110:111], v[110:111], v[114:115]
	v_mul_f32_e32 v114, v53, v53
	v_mul_f32_e32 v117, v50, v50
	v_pk_fma_f32 v[114:115], v[52:53], v[52:53], v[114:115] op_sel_hi:[1,1,0]
	v_mul_f32_e32 v116, v55, v55
	v_mul_f32_e32 v118, v51, v51
	v_mov_b32_e32 v115, v117
	v_pk_fma_f32 v[116:117], v[54:55], v[54:55], v[116:117] op_sel_hi:[1,1,0]
	s_nop 0
	v_mov_b32_e32 v117, v118
	v_pk_add_f32 v[114:115], v[114:115], v[116:117]
	s_nop 0
	v_pk_add_f32 v[110:111], v[110:111], v[114:115]
	s_nop 0
	v_add_f32_e32 v97, v110, v111
	ds_bpermute_b32 v110, v84, v97
	s_waitcnt lgkmcnt(0)
	v_add_f32_e32 v97, v97, v110
	ds_bpermute_b32 v110, v85, v97
	s_waitcnt lgkmcnt(0)
	v_add_f32_e32 v97, v97, v110
	ds_bpermute_b32 v110, v86, v97
	s_waitcnt lgkmcnt(0)
	v_add_f32_e32 v97, v97, v110
	ds_bpermute_b32 v110, v87, v97
	s_waitcnt lgkmcnt(0)
	v_add_f32_e32 v97, v97, v110
	ds_bpermute_b32 v110, v88, v97
	s_waitcnt lgkmcnt(0)
	v_add_f32_e32 v97, v97, v110
	ds_bpermute_b32 v114, v89, v97
	v_lshl_add_u64 v[110:111], v[78:79], 0, v[68:69]
	v_add_co_u32_e64 v110, s[6:7], s66, v110
	s_waitcnt lgkmcnt(0)
	v_add_f32_e32 v97, v97, v114
	v_fmamk_f32 v97, v97, 0x3a800000, v94
	v_mul_f32_e32 v114, 0x4b800000, v97
	v_cmp_gt_f32_e64 s[0:1], s62, v97
	v_addc_co_u32_e64 v111, s[6:7], 0, v111, s[6:7]
	s_nop 0
	v_cndmask_b32_e64 v97, v97, v114, s[0:1]
	v_rsq_f32_e32 v97, v97
	s_nop 0
	v_mul_f32_e32 v114, 0x45800000, v97
	v_cndmask_b32_e64 v114, v97, v114, s[0:1]
	v_pk_mul_f32 v[62:63], v[62:63], v[114:115] op_sel_hi:[1,0]
	v_pk_mul_f32 v[60:61], v[60:61], v[114:115] op_sel_hi:[1,0]
	s_waitcnt vmcnt(2)
	v_pk_mul_f32 v[62:63], v[100:101], v[62:63]
	v_pk_mul_f32 v[60:61], v[98:99], v[60:61]
	s_waitcnt vmcnt(1)
	v_pk_add_f32 v[100:101], v[102:103], 1.0 op_sel_hi:[1,0]
	v_pk_add_f32 v[98:99], v[104:105], 1.0 op_sel_hi:[1,0]
	s_waitcnt vmcnt(0)
	v_pk_fma_f32 v[60:61], v[100:101], v[60:61], v[106:107]
	v_pk_fma_f32 v[62:63], v[98:99], v[62:63], v[108:109]
	v_cvt_pk_bf16_f32 v60, v60, v61
	v_lshl_add_u64 v[106:107], v[112:113], 0, s[36:37]
	v_cvt_pk_bf16_f32 v61, v62, v63
	global_store_dwordx2 v[110:111], v[60:61], off
	s_nop 1
	v_mov_b64_e32 v[60:61], v[120:121]
	v_mov_b64_e32 v[62:63], v[122:123]
	v_mov_b64_e32 v[98:99], v[124:125]
	v_mov_b64_e32 v[100:101], v[126:127]
	v_mov_b64_e32 v[102:103], v[128:129]
	v_mov_b64_e32 v[104:105], v[130:131]
	v_pk_mul_f32 v[58:59], v[58:59], v[114:115] op_sel_hi:[1,0]
	v_pk_mul_f32 v[56:57], v[56:57], v[114:115] op_sel_hi:[1,0]
	v_pk_mul_f32 v[54:55], v[54:55], v[114:115] op_sel_hi:[1,0]
	v_pk_mul_f32 v[52:53], v[52:53], v[114:115] op_sel_hi:[1,0]
	v_pk_mul_f32 v[50:51], v[50:51], v[114:115] op_sel_hi:[1,0]
	v_pk_mul_f32 v[48:49], v[48:49], v[114:115] op_sel_hi:[1,0]
	v_pk_mul_f32 v[56:57], v[60:61], v[56:57]
	v_pk_mul_f32 v[58:59], v[62:63], v[58:59]
	v_pk_add_f32 v[62:63], v[98:99], 1.0 op_sel_hi:[1,0]
	v_pk_add_f32 v[60:61], v[100:101], 1.0 op_sel_hi:[1,0]
	v_pk_fma_f32 v[56:57], v[62:63], v[56:57], v[102:103]
	v_pk_fma_f32 v[58:59], v[60:61], v[58:59], v[104:105]
	v_cvt_pk_bf16_f32 v56, v56, v57
	s_nop 0
	v_cvt_pk_bf16_f32 v57, v58, v59
	global_store_dwordx2 v[110:111], v[56:57], off offset:512
	s_nop 1
	v_mov_b64_e32 v[56:57], v[132:133]
	v_mov_b64_e32 v[58:59], v[134:135]
	v_mov_b64_e32 v[60:61], v[136:137]
	v_mov_b64_e32 v[62:63], v[138:139]
	v_mov_b64_e32 v[98:99], v[140:141]
	v_mov_b64_e32 v[100:101], v[142:143]
	v_pk_mul_f32 v[52:53], v[52:53], v[56:57]
	v_pk_mul_f32 v[54:55], v[54:55], v[58:59]
	v_pk_add_f32 v[58:59], v[60:61], 1.0 op_sel_hi:[1,0]
	v_pk_add_f32 v[56:57], v[62:63], 1.0 op_sel_hi:[1,0]
	v_pk_fma_f32 v[52:53], v[52:53], v[58:59], v[98:99]
	v_pk_fma_f32 v[54:55], v[54:55], v[56:57], v[100:101]
	v_cvt_pk_bf16_f32 v52, v52, v53
	s_nop 0
	v_cvt_pk_bf16_f32 v53, v54, v55
	global_store_dwordx2 v[110:111], v[52:53], off offset:1024
	s_nop 1
	v_mov_b64_e32 v[52:53], v[144:145]
	v_mov_b64_e32 v[54:55], v[146:147]
	v_mov_b64_e32 v[56:57], v[148:149]
	v_mov_b64_e32 v[58:59], v[150:151]
	v_mov_b64_e32 v[60:61], v[152:153]
	v_mov_b64_e32 v[62:63], v[154:155]
	v_pk_mul_f32 v[48:49], v[48:49], v[52:53]
	v_pk_mul_f32 v[50:51], v[50:51], v[54:55]
	v_pk_add_f32 v[54:55], v[56:57], 1.0 op_sel_hi:[1,0]
	v_pk_add_f32 v[52:53], v[58:59], 1.0 op_sel_hi:[1,0]
	v_pk_fma_f32 v[48:49], v[48:49], v[54:55], v[60:61]
	v_pk_fma_f32 v[50:51], v[50:51], v[52:53], v[62:63]
	v_cvt_pk_bf16_f32 v48, v48, v49
	s_nop 0
	v_cvt_pk_bf16_f32 v49, v50, v51
	global_store_dwordx2 v[110:111], v[48:49], off offset:1536
	s_and_saveexec_b64 s[6:7], s[4:5]
	s_cbranch_execz .LBB0_148
	v_min_i32_e32 v48, 0x10000, v96
	v_ashrrev_i32_e32 v48, 12, v48
	v_mul_i32_i24_e32 v48, 0x1800, v48
	v_ashrrev_i32_e32 v49, 31, v48
	v_lshl_add_u64 v[48:49], v[48:49], 2, s[24:25]
	v_lshl_add_u64 v[60:61], v[48:49], 0, v[66:67]
	v_add_co_u32_e64 v52, s[0:1], s63, v60
	v_lshl_add_u64 v[156:157], v[60:61], 0, s[36:37]
	global_load_dwordx4 v[120:123], v[72:73], off offset:1024
	global_load_dwordx4 v[124:127], v[156:157], off offset:1024
	global_load_dwordx4 v[128:131], v[60:61], off offset:1024
	global_load_dwordx4 v[132:135], v[72:73], off offset:2048
	global_load_dwordx4 v[136:139], v[156:157], off offset:2048
	global_load_dwordx4 v[140:143], v[60:61], off offset:2048
	global_load_dwordx4 v[144:147], v[72:73], off offset:3072
	global_load_dwordx4 v[148:151], v[156:157], off offset:3072
	global_load_dwordx4 v[152:155], v[60:61], off offset:3072
	global_load_dwordx4 v[48:51], v[72:73], off
	s_nop 0
	v_addc_co_u32_e64 v53, s[0:1], 0, v61, s[0:1]
	global_load_dwordx4 v[52:55], v[52:53], off
	s_nop 0
	global_load_dwordx4 v[56:59], v[60:61], off
	v_pk_mul_f32 v[62:63], v[46:47], v[46:47]
	v_pk_mul_f32 v[96:97], v[44:45], v[44:45]
	s_waitcnt vmcnt(1)
	v_pk_add_f32 v[52:53], v[52:53], 1.0 op_sel_hi:[1,0]
	v_pk_mov_b32 v[98:99], v[96:97], v[62:63] op_sel:[1,0]
	v_mov_b32_e32 v97, v63
	v_pk_add_f32 v[62:63], v[98:99], v[96:97]
	v_pk_mul_f32 v[96:97], v[42:43], v[42:43]
	v_pk_add_f32 v[62:63], v[62:63], v[62:63] op_sel_hi:[0,1]
	v_pk_mul_f32 v[98:99], v[40:41], v[40:41]
	v_mul_f32_e32 v62, v36, v36
	v_pk_mov_b32 v[100:101], v[98:99], v[96:97] op_sel:[1,0]
	v_mov_b32_e32 v99, v97
	v_pk_add_f32 v[96:97], v[100:101], v[98:99]
	v_pk_fma_f32 v[98:99], v[36:37], v[36:37], v[62:63] op_sel_hi:[1,1,0]
	v_mul_f32_e32 v62, v38, v38
	v_pk_add_f32 v[96:97], v[96:97], v[96:97] op_sel_hi:[0,1]
	v_pk_fma_f32 v[100:101], v[38:39], v[38:39], v[62:63] op_sel_hi:[1,1,0]
	v_mul_f32_e32 v98, v32, v32
	v_mul_f32_e32 v100, v33, v33
	v_mul_f32_e32 v96, v34, v34
	v_mul_f32_e32 v62, v35, v35
	v_pk_add_f32 v[98:99], v[98:99], v[100:101]
	v_pk_add_f32 v[62:63], v[96:97], v[62:63]
	v_pk_add_f32 v[54:55], v[54:55], 1.0 op_sel_hi:[1,0]
	v_pk_add_f32 v[62:63], v[98:99], v[62:63]
	s_nop 0
	v_add_f32_e32 v62, v62, v63
	ds_bpermute_b32 v63, v84, v62
	s_waitcnt lgkmcnt(0)
	v_add_f32_e32 v62, v62, v63
	ds_bpermute_b32 v63, v85, v62
	s_waitcnt lgkmcnt(0)
	v_add_f32_e32 v62, v62, v63
	ds_bpermute_b32 v63, v86, v62
	s_waitcnt lgkmcnt(0)
	v_add_f32_e32 v62, v62, v63
	ds_bpermute_b32 v63, v87, v62
	s_waitcnt lgkmcnt(0)
	v_add_f32_e32 v62, v62, v63
	ds_bpermute_b32 v63, v88, v62
	s_waitcnt lgkmcnt(0)
	v_add_f32_e32 v96, v62, v63
	ds_bpermute_b32 v97, v89, v96
	v_lshl_add_u64 v[62:63], v[76:77], 0, v[68:69]
	v_add_co_u32_e64 v62, s[4:5], s66, v62
	s_waitcnt lgkmcnt(0)
	v_add_f32_e32 v96, v96, v97
	v_fmamk_f32 v96, v96, 0x3a800000, v94
	v_mul_f32_e32 v97, 0x4b800000, v96
	v_cmp_gt_f32_e64 s[0:1], s62, v96
	v_addc_co_u32_e64 v63, s[4:5], 0, v63, s[4:5]
	s_nop 0
	v_cndmask_b32_e64 v96, v96, v97, s[0:1]
	v_rsq_f32_e32 v96, v96
	s_nop 0
	v_mul_f32_e32 v97, 0x45800000, v96
	v_cndmask_b32_e64 v96, v96, v97, s[0:1]
	v_pk_mul_f32 v[100:101], v[44:45], v[96:97] op_sel_hi:[1,0]
	v_pk_mul_f32 v[98:99], v[46:47], v[96:97] op_sel_hi:[1,0]
	v_pk_mul_f32 v[48:49], v[48:49], v[100:101]
	v_pk_mul_f32 v[50:51], v[50:51], v[98:99]
	s_waitcnt vmcnt(0)
	v_pk_fma_f32 v[48:49], v[52:53], v[48:49], v[56:57]
	v_pk_fma_f32 v[50:51], v[54:55], v[50:51], v[58:59]
	v_cvt_pk_bf16_f32 v48, v48, v49
	v_lshl_add_u64 v[98:99], v[60:61], 0, s[36:37]
	v_cvt_pk_bf16_f32 v49, v50, v51
	global_store_dwordx2 v[62:63], v[48:49], off
	s_nop 1
	v_mov_b64_e32 v[48:49], v[120:121]
	v_mov_b64_e32 v[50:51], v[122:123]
	v_mov_b64_e32 v[52:53], v[124:125]
	v_mov_b64_e32 v[54:55], v[126:127]
	v_mov_b64_e32 v[56:57], v[128:129]
	v_mov_b64_e32 v[58:59], v[130:131]
	v_pk_mul_f32 v[102:103], v[40:41], v[96:97] op_sel_hi:[1,0]
	v_pk_mul_f32 v[100:101], v[42:43], v[96:97] op_sel_hi:[1,0]
	v_pk_mul_f32 v[48:49], v[48:49], v[102:103]
	v_pk_add_f32 v[52:53], v[52:53], 1.0 op_sel_hi:[1,0]
	v_pk_mul_f32 v[50:51], v[50:51], v[100:101]
	v_pk_add_f32 v[54:55], v[54:55], 1.0 op_sel_hi:[1,0]
	v_pk_fma_f32 v[48:49], v[52:53], v[48:49], v[56:57]
	v_pk_fma_f32 v[50:51], v[54:55], v[50:51], v[58:59]
	v_cvt_pk_bf16_f32 v48, v48, v49
	v_pk_mul_f32 v[102:103], v[36:37], v[96:97] op_sel_hi:[1,0]
	v_cvt_pk_bf16_f32 v49, v50, v51
	global_store_dwordx2 v[62:63], v[48:49], off offset:512
	s_nop 1
	v_mov_b64_e32 v[48:49], v[132:133]
	v_mov_b64_e32 v[50:51], v[134:135]
	v_mov_b64_e32 v[52:53], v[136:137]
	v_mov_b64_e32 v[54:55], v[138:139]
	v_mov_b64_e32 v[56:57], v[140:141]
	v_mov_b64_e32 v[58:59], v[142:143]
	v_pk_mul_f32 v[100:101], v[38:39], v[96:97] op_sel_hi:[1,0]
	v_pk_mul_f32 v[48:49], v[102:103], v[48:49]
	v_pk_add_f32 v[52:53], v[52:53], 1.0 op_sel_hi:[1,0]
	v_pk_mul_f32 v[50:51], v[100:101], v[50:51]
	v_pk_add_f32 v[54:55], v[54:55], 1.0 op_sel_hi:[1,0]
	v_pk_fma_f32 v[48:49], v[48:49], v[52:53], v[56:57]
	v_pk_fma_f32 v[50:51], v[50:51], v[54:55], v[58:59]
	v_cvt_pk_bf16_f32 v48, v48, v49
	s_nop 0
	v_cvt_pk_bf16_f32 v49, v50, v51
	global_store_dwordx2 v[62:63], v[48:49], off offset:1024
	s_nop 1
	v_mov_b64_e32 v[48:49], v[144:145]
	v_mov_b64_e32 v[50:51], v[146:147]
	v_mov_b64_e32 v[52:53], v[148:149]
	v_mov_b64_e32 v[54:55], v[150:151]
	v_mov_b64_e32 v[56:57], v[152:153]
	v_mov_b64_e32 v[58:59], v[154:155]
	v_pk_mul_f32 v[60:61], v[34:35], v[96:97] op_sel_hi:[1,0]
	v_pk_mul_f32 v[96:97], v[32:33], v[96:97] op_sel_hi:[1,0]
	v_pk_mul_f32 v[50:51], v[60:61], v[50:51]
	v_pk_mul_f32 v[48:49], v[96:97], v[48:49]
	v_pk_add_f32 v[52:53], v[52:53], 1.0 op_sel_hi:[1,0]
	v_pk_add_f32 v[54:55], v[54:55], 1.0 op_sel_hi:[1,0]
	v_pk_fma_f32 v[48:49], v[48:49], v[52:53], v[56:57]
	v_pk_fma_f32 v[50:51], v[50:51], v[54:55], v[58:59]
	v_cvt_pk_bf16_f32 v48, v48, v49
	s_nop 0
	v_cvt_pk_bf16_f32 v49, v50, v51
	global_store_dwordx2 v[62:63], v[48:49], off offset:1536
	s_or_b64 exec, exec, s[6:7]
	s_and_saveexec_b64 s[4:5], s[2:3]
	s_cbranch_execnz .LBB0_149

.LBB0_149:
	v_min_i32_e32 v48, 0x10000, v82
	v_ashrrev_i32_e32 v48, 12, v48
	v_mul_i32_i24_e32 v48, 0x1800, v48
	v_ashrrev_i32_e32 v49, 31, v48
	v_lshl_add_u64 v[48:49], v[48:49], 2, s[24:25]
	v_lshl_add_u64 v[60:61], v[48:49], 0, v[66:67]
	v_add_co_u32_e64 v52, s[0:1], s63, v60
	v_lshl_add_u64 v[156:157], v[60:61], 0, s[36:37]
	global_load_dwordx4 v[120:123], v[72:73], off offset:1024
	global_load_dwordx4 v[124:127], v[156:157], off offset:1024
	global_load_dwordx4 v[128:131], v[60:61], off offset:1024
	global_load_dwordx4 v[132:135], v[72:73], off offset:2048
	global_load_dwordx4 v[136:139], v[156:157], off offset:2048
	global_load_dwordx4 v[140:143], v[60:61], off offset:2048
	global_load_dwordx4 v[144:147], v[72:73], off offset:3072
	global_load_dwordx4 v[148:151], v[156:157], off offset:3072
	global_load_dwordx4 v[152:155], v[60:61], off offset:3072
	global_load_dwordx4 v[48:51], v[72:73], off
	s_nop 0
	v_addc_co_u32_e64 v53, s[0:1], 0, v61, s[0:1]
	global_load_dwordx4 v[52:55], v[52:53], off
	s_nop 0
	global_load_dwordx4 v[56:59], v[60:61], off
	v_pk_mul_f32 v[62:63], v[30:31], v[30:31]
	v_pk_mul_f32 v[96:97], v[28:29], v[28:29]
	v_pk_mul_f32 v[98:99], v[26:27], v[26:27]
	v_pk_mul_f32 v[100:101], v[24:25], v[24:25]
	v_pk_mov_b32 v[106:107], v[96:97], v[62:63] op_sel:[1,0]
	v_mov_b32_e32 v97, v63
	v_pk_mov_b32 v[62:63], v[100:101], v[98:99] op_sel:[1,0]
	v_mov_b32_e32 v101, v99
	v_mul_f32_e32 v102, v20, v20
	v_mul_f32_e32 v104, v22, v22
	v_pk_add_f32 v[96:97], v[106:107], v[96:97]
	v_pk_add_f32 v[62:63], v[62:63], v[100:101]
	v_pk_fma_f32 v[98:99], v[20:21], v[20:21], v[102:103] op_sel_hi:[1,1,0]
	v_pk_fma_f32 v[102:103], v[22:23], v[22:23], v[104:105] op_sel_hi:[1,1,0]
	v_pk_add_f32 v[96:97], v[96:97], v[96:97] op_sel_hi:[0,1]
	v_pk_add_f32 v[62:63], v[62:63], v[62:63] op_sel_hi:[0,1]
	v_mul_f32_e32 v98, v16, v16
	v_mul_f32_e32 v102, v17, v17
	v_mul_f32_e32 v62, v18, v18
	v_mul_f32_e32 v96, v19, v19
	v_pk_add_f32 v[98:99], v[98:99], v[102:103]
	v_pk_add_f32 v[62:63], v[62:63], v[96:97]
	s_waitcnt vmcnt(1)
	v_pk_add_f32 v[52:53], v[52:53], 1.0 op_sel_hi:[1,0]
	v_pk_add_f32 v[62:63], v[98:99], v[62:63]
	v_pk_add_f32 v[54:55], v[54:55], 1.0 op_sel_hi:[1,0]
	v_add_f32_e32 v62, v62, v63
	ds_bpermute_b32 v63, v84, v62
	s_waitcnt lgkmcnt(0)
	v_add_f32_e32 v62, v62, v63
	ds_bpermute_b32 v63, v85, v62
	s_waitcnt lgkmcnt(0)
	v_add_f32_e32 v62, v62, v63
	ds_bpermute_b32 v63, v86, v62
	s_waitcnt lgkmcnt(0)
	v_add_f32_e32 v62, v62, v63
	ds_bpermute_b32 v63, v87, v62
	s_waitcnt lgkmcnt(0)
	v_add_f32_e32 v62, v62, v63
	ds_bpermute_b32 v63, v88, v62
	s_waitcnt lgkmcnt(0)
	v_add_f32_e32 v62, v62, v63
	ds_bpermute_b32 v63, v89, v62
	s_waitcnt lgkmcnt(0)
	v_add_f32_e32 v62, v62, v63
	v_fmamk_f32 v62, v62, 0x3a800000, v94
	v_mul_f32_e32 v63, 0x4b800000, v62
	v_cmp_gt_f32_e64 s[0:1], s62, v62
	s_nop 1
	v_cndmask_b32_e64 v62, v62, v63, s[0:1]
	v_rsq_f32_e32 v96, v62
	v_lshlrev_b64 v[62:63], 11, v[82:83]
	v_lshl_add_u64 v[62:63], v[70:71], 0, v[62:63]
	v_mul_f32_e32 v82, 0x45800000, v96
	v_cndmask_b32_e64 v82, v96, v82, s[0:1]
	v_pk_mul_f32 v[98:99], v[28:29], v[82:83] op_sel_hi:[1,0]
	v_pk_mul_f32 v[96:97], v[30:31], v[82:83] op_sel_hi:[1,0]
	v_pk_mul_f32 v[48:49], v[48:49], v[98:99]
	v_pk_mul_f32 v[50:51], v[50:51], v[96:97]
	s_waitcnt vmcnt(0)
	v_pk_fma_f32 v[48:49], v[52:53], v[48:49], v[56:57]
	v_pk_fma_f32 v[50:51], v[54:55], v[50:51], v[58:59]
	v_cvt_pk_bf16_f32 v48, v48, v49
	v_lshl_add_u64 v[96:97], v[60:61], 0, s[36:37]
	v_cvt_pk_bf16_f32 v49, v50, v51
	global_store_dwordx2 v[62:63], v[48:49], off
	s_nop 1
	v_mov_b64_e32 v[48:49], v[120:121]
	v_mov_b64_e32 v[50:51], v[122:123]
	v_mov_b64_e32 v[52:53], v[124:125]
	v_mov_b64_e32 v[54:55], v[126:127]
	v_mov_b64_e32 v[56:57], v[128:129]
	v_mov_b64_e32 v[58:59], v[130:131]
	v_pk_mul_f32 v[100:101], v[24:25], v[82:83] op_sel_hi:[1,0]
	v_pk_mul_f32 v[98:99], v[26:27], v[82:83] op_sel_hi:[1,0]
	v_pk_add_f32 v[52:53], v[52:53], 1.0 op_sel_hi:[1,0]
	v_pk_mul_f32 v[48:49], v[48:49], v[100:101]
	v_pk_mul_f32 v[50:51], v[50:51], v[98:99]
	v_pk_add_f32 v[54:55], v[54:55], 1.0 op_sel_hi:[1,0]
	v_pk_fma_f32 v[48:49], v[52:53], v[48:49], v[56:57]
	v_pk_fma_f32 v[50:51], v[54:55], v[50:51], v[58:59]
	v_cvt_pk_bf16_f32 v48, v48, v49
	v_pk_mul_f32 v[100:101], v[20:21], v[82:83] op_sel_hi:[1,0]
	v_cvt_pk_bf16_f32 v49, v50, v51
	global_store_dwordx2 v[62:63], v[48:49], off offset:512
	s_nop 1
	v_mov_b64_e32 v[48:49], v[132:133]
	v_mov_b64_e32 v[50:51], v[134:135]
	v_mov_b64_e32 v[52:53], v[136:137]
	v_mov_b64_e32 v[54:55], v[138:139]
	v_mov_b64_e32 v[56:57], v[140:141]
	v_mov_b64_e32 v[58:59], v[142:143]
	v_pk_mul_f32 v[98:99], v[22:23], v[82:83] op_sel_hi:[1,0]
	v_pk_mul_f32 v[48:49], v[100:101], v[48:49]
	v_pk_add_f32 v[52:53], v[52:53], 1.0 op_sel_hi:[1,0]
	v_pk_mul_f32 v[50:51], v[98:99], v[50:51]
	v_pk_add_f32 v[54:55], v[54:55], 1.0 op_sel_hi:[1,0]
	v_pk_fma_f32 v[48:49], v[48:49], v[52:53], v[56:57]
	v_pk_fma_f32 v[50:51], v[50:51], v[54:55], v[58:59]
	v_cvt_pk_bf16_f32 v48, v48, v49
	s_nop 0
	v_cvt_pk_bf16_f32 v49, v50, v51
	global_store_dwordx2 v[62:63], v[48:49], off offset:1024
	s_nop 1
	v_mov_b64_e32 v[48:49], v[144:145]
	v_mov_b64_e32 v[50:51], v[146:147]
	v_mov_b64_e32 v[52:53], v[148:149]
	v_mov_b64_e32 v[54:55], v[150:151]
	v_mov_b64_e32 v[56:57], v[152:153]
	v_mov_b64_e32 v[58:59], v[154:155]
	v_pk_mul_f32 v[60:61], v[18:19], v[82:83] op_sel_hi:[1,0]
	v_pk_mul_f32 v[82:83], v[16:17], v[82:83] op_sel_hi:[1,0]
	v_pk_mul_f32 v[50:51], v[60:61], v[50:51]
	v_pk_mul_f32 v[48:49], v[82:83], v[48:49]
	v_pk_add_f32 v[52:53], v[52:53], 1.0 op_sel_hi:[1,0]
	v_pk_add_f32 v[54:55], v[54:55], 1.0 op_sel_hi:[1,0]
	v_pk_fma_f32 v[48:49], v[48:49], v[52:53], v[56:57]
	v_pk_fma_f32 v[50:51], v[50:51], v[54:55], v[58:59]
	v_cvt_pk_bf16_f32 v48, v48, v49
	s_nop 0
	v_cvt_pk_bf16_f32 v49, v50, v51
	global_store_dwordx2 v[62:63], v[48:49], off offset:1536
	s_or_b64 exec, exec, s[4:5]
	s_and_saveexec_b64 s[0:1], vcc
	s_cbranch_execz .LBB0_138
.LBB0_150:
	v_min_i32_e32 v48, 0x10000, v80
	v_ashrrev_i32_e32 v48, 12, v48
	v_mul_i32_i24_e32 v48, 0x1800, v48
	v_ashrrev_i32_e32 v49, 31, v48
	v_lshl_add_u64 v[48:49], v[48:49], 2, s[24:25]
	v_lshl_add_u64 v[60:61], v[48:49], 0, v[66:67]
	v_add_co_u32_e32 v52, vcc, s63, v60
	v_lshl_add_u64 v[156:157], v[60:61], 0, s[36:37]
	global_load_dwordx4 v[120:123], v[72:73], off offset:1024
	global_load_dwordx4 v[124:127], v[156:157], off offset:1024
	global_load_dwordx4 v[128:131], v[60:61], off offset:1024
	global_load_dwordx4 v[132:135], v[72:73], off offset:2048
	global_load_dwordx4 v[136:139], v[156:157], off offset:2048
	global_load_dwordx4 v[140:143], v[60:61], off offset:2048
	global_load_dwordx4 v[144:147], v[72:73], off offset:3072
	global_load_dwordx4 v[148:151], v[156:157], off offset:3072
	global_load_dwordx4 v[152:155], v[60:61], off offset:3072
	global_load_dwordx4 v[48:51], v[72:73], off
	s_nop 0
	v_addc_co_u32_e32 v53, vcc, 0, v61, vcc
	global_load_dwordx4 v[52:55], v[52:53], off
	s_nop 0
	global_load_dwordx4 v[56:59], v[60:61], off
	v_pk_mul_f32 v[62:63], v[14:15], v[14:15]
	v_pk_mul_f32 v[82:83], v[12:13], v[12:13]
	v_pk_mul_f32 v[96:97], v[10:11], v[10:11]
	v_pk_mul_f32 v[98:99], v[8:9], v[8:9]
	v_pk_mov_b32 v[104:105], v[82:83], v[62:63] op_sel:[1,0]
	v_mov_b32_e32 v83, v63
	v_pk_mov_b32 v[62:63], v[98:99], v[96:97] op_sel:[1,0]
	v_mov_b32_e32 v99, v97
	v_mul_f32_e32 v100, v4, v4
	v_mul_f32_e32 v102, v6, v6
	v_pk_add_f32 v[82:83], v[104:105], v[82:83]
	v_pk_add_f32 v[62:63], v[62:63], v[98:99]
	v_pk_fma_f32 v[96:97], v[4:5], v[4:5], v[100:101] op_sel_hi:[1,1,0]
	v_pk_fma_f32 v[100:101], v[6:7], v[6:7], v[102:103] op_sel_hi:[1,1,0]
	v_pk_add_f32 v[82:83], v[82:83], v[82:83] op_sel_hi:[0,1]
	v_pk_add_f32 v[62:63], v[62:63], v[62:63] op_sel_hi:[0,1]
	v_mul_f32_e32 v96, v0, v0
	v_mul_f32_e32 v100, v1, v1
	v_mul_f32_e32 v62, v2, v2
	v_mul_f32_e32 v82, v3, v3
	v_pk_add_f32 v[96:97], v[96:97], v[100:101]
	v_pk_add_f32 v[62:63], v[62:63], v[82:83]
	s_waitcnt vmcnt(1)
	v_pk_add_f32 v[52:53], v[52:53], 1.0 op_sel_hi:[1,0]
	v_pk_add_f32 v[62:63], v[96:97], v[62:63]
	v_pk_add_f32 v[54:55], v[54:55], 1.0 op_sel_hi:[1,0]
	v_add_f32_e32 v62, v62, v63
	ds_bpermute_b32 v63, v84, v62
	s_waitcnt lgkmcnt(0)
	v_add_f32_e32 v62, v62, v63
	ds_bpermute_b32 v63, v85, v62
	s_waitcnt lgkmcnt(0)
	v_add_f32_e32 v62, v62, v63
	ds_bpermute_b32 v63, v86, v62
	s_waitcnt lgkmcnt(0)
	v_add_f32_e32 v62, v62, v63
	ds_bpermute_b32 v63, v87, v62
	s_waitcnt lgkmcnt(0)
	v_add_f32_e32 v62, v62, v63
	ds_bpermute_b32 v63, v88, v62
	s_waitcnt lgkmcnt(0)
	v_add_f32_e32 v62, v62, v63
	ds_bpermute_b32 v63, v89, v62
	s_waitcnt lgkmcnt(0)
	v_add_f32_e32 v62, v62, v63
	v_fmamk_f32 v62, v62, 0x3a800000, v94
	v_mul_f32_e32 v63, 0x4b800000, v62
	v_cmp_gt_f32_e32 vcc, s62, v62
	s_nop 1
	v_cndmask_b32_e32 v62, v62, v63, vcc
	v_rsq_f32_e32 v82, v62
	v_lshlrev_b64 v[62:63], 11, v[80:81]
	v_lshl_add_u64 v[62:63], v[70:71], 0, v[62:63]
	v_mul_f32_e32 v80, 0x45800000, v82
	v_cndmask_b32_e32 v80, v82, v80, vcc
	v_pk_mul_f32 v[96:97], v[12:13], v[80:81] op_sel_hi:[1,0]
	v_pk_mul_f32 v[82:83], v[14:15], v[80:81] op_sel_hi:[1,0]
	v_pk_mul_f32 v[48:49], v[48:49], v[96:97]
	v_pk_mul_f32 v[50:51], v[50:51], v[82:83]
	s_waitcnt vmcnt(0)
	v_pk_fma_f32 v[48:49], v[52:53], v[48:49], v[56:57]
	v_pk_fma_f32 v[50:51], v[54:55], v[50:51], v[58:59]
	v_cvt_pk_bf16_f32 v48, v48, v49
	v_lshl_add_u64 v[82:83], v[60:61], 0, s[36:37]
	v_cvt_pk_bf16_f32 v49, v50, v51
	global_store_dwordx2 v[62:63], v[48:49], off
	s_nop 1
	v_mov_b64_e32 v[48:49], v[120:121]
	v_mov_b64_e32 v[50:51], v[122:123]
	v_mov_b64_e32 v[52:53], v[124:125]
	v_mov_b64_e32 v[54:55], v[126:127]
	v_mov_b64_e32 v[56:57], v[128:129]
	v_mov_b64_e32 v[58:59], v[130:131]
	v_pk_mul_f32 v[98:99], v[8:9], v[80:81] op_sel_hi:[1,0]
	v_pk_mul_f32 v[96:97], v[10:11], v[80:81] op_sel_hi:[1,0]
	v_pk_add_f32 v[52:53], v[52:53], 1.0 op_sel_hi:[1,0]
	v_pk_mul_f32 v[48:49], v[48:49], v[98:99]
	v_pk_mul_f32 v[50:51], v[50:51], v[96:97]
	v_pk_add_f32 v[54:55], v[54:55], 1.0 op_sel_hi:[1,0]
	v_pk_fma_f32 v[48:49], v[52:53], v[48:49], v[56:57]
	v_pk_fma_f32 v[50:51], v[54:55], v[50:51], v[58:59]
	v_cvt_pk_bf16_f32 v48, v48, v49
	v_pk_mul_f32 v[98:99], v[4:5], v[80:81] op_sel_hi:[1,0]
	v_cvt_pk_bf16_f32 v49, v50, v51
	global_store_dwordx2 v[62:63], v[48:49], off offset:512
	s_nop 1
	v_mov_b64_e32 v[48:49], v[132:133]
	v_mov_b64_e32 v[50:51], v[134:135]
	v_mov_b64_e32 v[52:53], v[136:137]
	v_mov_b64_e32 v[54:55], v[138:139]
	v_mov_b64_e32 v[56:57], v[140:141]
	v_mov_b64_e32 v[58:59], v[142:143]
	v_pk_mul_f32 v[96:97], v[6:7], v[80:81] op_sel_hi:[1,0]
	v_pk_mul_f32 v[48:49], v[98:99], v[48:49]
	v_pk_add_f32 v[52:53], v[52:53], 1.0 op_sel_hi:[1,0]
	v_pk_mul_f32 v[50:51], v[96:97], v[50:51]
	v_pk_add_f32 v[54:55], v[54:55], 1.0 op_sel_hi:[1,0]
	v_pk_fma_f32 v[48:49], v[48:49], v[52:53], v[56:57]
	v_pk_fma_f32 v[50:51], v[50:51], v[54:55], v[58:59]
	v_cvt_pk_bf16_f32 v48, v48, v49
	s_nop 0
	v_cvt_pk_bf16_f32 v49, v50, v51
	global_store_dwordx2 v[62:63], v[48:49], off offset:1024
	s_nop 1
	v_mov_b64_e32 v[48:49], v[144:145]
	v_mov_b64_e32 v[50:51], v[146:147]
	v_mov_b64_e32 v[52:53], v[148:149]
	v_mov_b64_e32 v[54:55], v[150:151]
	v_mov_b64_e32 v[56:57], v[152:153]
	v_mov_b64_e32 v[58:59], v[154:155]
	v_pk_mul_f32 v[60:61], v[2:3], v[80:81] op_sel_hi:[1,0]
	v_pk_mul_f32 v[80:81], v[0:1], v[80:81] op_sel_hi:[1,0]
	v_pk_mul_f32 v[50:51], v[60:61], v[50:51]
	v_pk_mul_f32 v[48:49], v[80:81], v[48:49]
	v_pk_add_f32 v[52:53], v[52:53], 1.0 op_sel_hi:[1,0]
	v_pk_add_f32 v[54:55], v[54:55], 1.0 op_sel_hi:[1,0]
	v_pk_fma_f32 v[48:49], v[48:49], v[52:53], v[56:57]
	v_pk_fma_f32 v[50:51], v[50:51], v[54:55], v[58:59]
	v_cvt_pk_bf16_f32 v48, v48, v49
	s_nop 0
	v_cvt_pk_bf16_f32 v49, v50, v51
	global_store_dwordx2 v[62:63], v[48:49], off offset:1536
	s_branch .LBB0_138
